# attention: K/V tile prefetch issued a full tile ahead; units remapped so each XCD shares K/V streams; grid sync replaced by per-XCC flag fan-out barrier
# speedup vs baseline: 1.0323x; 1.0122x over previous
; __global__ void __launch_bounds__(NTHREADS, 2) mega(Params p) {
;     ...
;     grid.sync();
.LBB0_130:
	s_or_b64 exec, exec, s[0:1]
	v_lshrrev_b32_e32 v1, 20, v0
	v_lshrrev_b32_e32 v0, 10, v0
	v_or_b32_e32 v0, v0, v1
	s_movk_i32 s0, 0x3ff
	v_and_or_b32 v0, v0, s0, v220
	v_cmp_eq_u32_e32 vcc, 0, v0
	s_waitcnt vmcnt(0) lgkmcnt(0)
	s_barrier
	s_and_saveexec_b64 s[0:1], vcc
	s_xor_b64 s[0:1], exec, s[0:1]
	s_cbranch_execz .LBB0_140
	buffer_wbl2 sc1
	s_waitcnt vmcnt(0)
	s_add_u32 s4, s88, 0x5000
	s_addc_u32 s5, s89, 0
	v_mov_b32_e32 v2, 0
	v_mov_b32_e32 v3, 1
	global_atomic_add v0, v2, v3, s[4:5] sc0
	s_lshl_b32 s7, s93, 8
	s_add_i32 s7, s7, 0x100
	v_mov_b32_e32 v4, s7
	s_waitcnt vmcnt(0)
	v_readfirstlane_b32 s6, v0
	s_nop 3
	s_add_i32 s6, s6, 1
	s_cmp_lg_u32 s6, s90
	s_cbranch_scc1 .Lgsync_spin
	global_store_dword v2, v3, s[4:5] offset:256 sc0 sc1
	global_store_dword v2, v3, s[4:5] offset:512 sc0 sc1
	global_store_dword v2, v3, s[4:5] offset:768 sc0 sc1
	global_store_dword v2, v3, s[4:5] offset:1024 sc0 sc1
	global_store_dword v2, v3, s[4:5] offset:1280 sc0 sc1
	global_store_dword v2, v3, s[4:5] offset:1536 sc0 sc1
	global_store_dword v2, v3, s[4:5] offset:1792 sc0 sc1
	global_store_dword v2, v3, s[4:5] offset:2048 sc0 sc1
	global_store_dword v2, v3, s[4:5] offset:2304 sc0 sc1
	global_store_dword v2, v3, s[4:5] offset:2560 sc0 sc1
	global_store_dword v2, v3, s[4:5] offset:2816 sc0 sc1
	global_store_dword v2, v3, s[4:5] offset:3072 sc0 sc1
	global_store_dword v2, v3, s[4:5] offset:3328 sc0 sc1
	global_store_dword v2, v3, s[4:5] offset:3584 sc0 sc1
	global_store_dword v2, v3, s[4:5] offset:3840 sc0 sc1
	s_add_u32 s8, s4, 0x1000
	s_addc_u32 s9, s5, 0
	global_store_dword v2, v3, s[8:9] sc0 sc1
	s_waitcnt vmcnt(0)
.Lgsync_spin:
	s_sleep 1
	global_load_dword v0, v4, s[4:5] sc1
	s_waitcnt vmcnt(0)
	v_cmp_eq_u32_e32 vcc, 0, v0
	s_cbranch_vccnz .Lgsync_spin
	buffer_inv sc1
	s_waitcnt vmcnt(0)

; __device__ __forceinline__ void attn_phase(const Params& p, int l, LAS unsigned char* lds, int tid) {
;     ...
;     for (int u = blockIdx.x; u < nunits; u += gridDim.x) {
;         const bool lat = u < 512;
;         const int v = lat ? u : u - 512;
;         const int b = lat ? (v >> 6) : (v >> 3), head = lat ? ((v >> 3) & 7) : (v & 7), qb = v & 7, kvh = head >> 2;
;         const size_t qrow = (size_t)(b * 8 + head) * TKV + (lat ? 256 + qb * 512 : 0);
;         const size_t orow = lat ? (size_t)(b * SEQ + qb * 512) : (size_t)(MX + b * CTX);
;         attn_unit(QS + qrow * 64, KS + (size_t)(b * 2 + kvh) * TKV * 64, VT + (size_t)(b * 2 + kvh) * 64 * TKV, lat ? TKV / 64 : CTX / 64, lat ? 512 : 256,
.LBB0_477:
	s_or_b64 exec, exec, s[4:5]
	s_mov_b32 s7, s101
	s_add_i32 s7, s7, s90
	s_cmp_ge_i32 s7, s6
	s_cbranch_scc1 .LBB0_491
.LBB0_478:
	s_mov_b32 s101, s7
	s_cmpk_lt_i32 s7, 0x200
	s_cbranch_scc0 .Lattn_noremap
	s_and_b32 s30, s7, 7
	s_bfe_u32 s31, s7, 0x50003
	s_lshr_b32 s28, s7, 8
	s_lshl_b32 s30, s30, 6
	s_lshr_b32 s29, s31, 3
	s_lshl_b32 s28, s28, 2
	s_add_i32 s28, s28, s29
	s_lshl_b32 s28, s28, 3
	s_and_b32 s31, s31, 7
	s_or_b32 s7, s30, s28
	s_or_b32 s7, s7, s31

; #define LAS __attribute__((address_space(3)))
; __device__ __forceinline__ void attn_unit(const bf16_t* Q, const bf16_t* K, const bf16_t* Vt, int ntiles, int nrows, bf16_t* O, float negM, LAS unsigned char* lds, int tid) {
;     ...
;     for (int t = 0; t < ntiles; ++t) {
;         const int cur = t & 1;
;         const bool more = (t + 1 < ntiles);
;         if (more) { kr = *(const u32x4*)(kg + (size_t)(t + 1) * 4096); vr = *(const u32x4*)(vg + (size_t)(t + 1) * 64); }
;         const LAS unsigned char* kb = lds + cur * 18432 + foff;
;         const LAS unsigned char* vb = kb + 9216;
;         bf16x8 kf0[4], kf1[4];
; #pragma unroll
;         for (int s = 0; s < 4; ++s) { kf0[s] = *(const LAS bf16x8*)(kb + s * 32); kf1[s] = *(const LAS bf16x8*)(kb + 32 * 144 + s * 32); }
;         bf16x8 pa[4], pb[4];
;         ATT_SCORES(qa, pa, lsa);
;         bf16x8 qc[4];
; #pragma unroll
;         for (int s = 0; s < 4; ++s) qc[s] = *(const LAS bf16x8*)(qlds + s * 1024);
;         ATT_SCORES(qc, pb, lsb);
; #pragma unroll
;         for (int s = 0; s < 4; ++s) {
;             const bf16x8 v0 = *(const LAS bf16x8*)(vb + s * 32), v1 = *(const LAS bf16x8*)(vb + 32 * 144 + s * 32);
;             oa0 = __builtin_amdgcn_mfma_f32_32x32x16_bf16(v0, pa[s], oa0, 0, 0, 0);
;             oa1 = __builtin_amdgcn_mfma_f32_32x32x16_bf16(v1, pa[s], oa1, 0, 0, 0);
;             ob0 = __builtin_amdgcn_mfma_f32_32x32x16_bf16(v0, pb[s], ob0, 0, 0, 0);
;             ob1 = __builtin_amdgcn_mfma_f32_32x32x16_bf16(v1, pb[s], ob1, 0, 0, 0);
;         }
;         if (more) { *(LAS u32x4*)(lds + (cur ^ 1) * 18432 + soff) = kr; *(LAS u32x4*)(lds + (cur ^ 1) * 18432 + 9216 + soff) = vr; }
.Lattn_tile:
	v_mfma_f32_32x32x16_bf16 v[128:143], v[80:83], v[96:99], v[0:15]
	ds_read_b128 v[80:83], v173 offset:4608
	v_exp_f32_e32 v112, v112
	v_exp_f32_e32 v113, v113
	v_mfma_f32_32x32x16_bf16 v[16:31], v[200:203], v[238:241], v[16:31]
	ds_read_b128 v[200:203], v173 offset:9216
	v_exp_f32_e32 v114, v114
	v_exp_f32_e32 v115, v115
	v_cvt_pk_bf16_f32 v216, v112, v113
	v_add_f32_e32 v194, v194, v112
	v_add_f32_e32 v226, v226, v113
	v_mfma_f32_32x32x16_bf16 v[128:143], v[84:87], v[100:103], v[128:143]
	ds_read_b128 v[84:87], v173 offset:4640
	v_exp_f32_e32 v116, v116
	v_exp_f32_e32 v117, v117
	v_cvt_pk_bf16_f32 v217, v114, v115
	v_add_f32_e32 v194, v194, v114
	v_add_f32_e32 v226, v226, v115
	v_mfma_f32_32x32x16_bf16 v[32:47], v[204:207], v[238:241], v[32:47]
	ds_read_b128 v[204:207], v173 offset:13824
	v_exp_f32_e32 v118, v118
	v_exp_f32_e32 v119, v119
	v_cvt_pk_bf16_f32 v218, v116, v117
	v_add_f32_e32 v194, v194, v116
	v_add_f32_e32 v226, v226, v117
	v_mfma_f32_32x32x16_bf16 v[128:143], v[88:91], v[104:107], v[128:143]
	ds_read_b128 v[88:91], v173 offset:4672
	v_exp_f32_e32 v120, v120
	v_exp_f32_e32 v121, v121
	v_cvt_pk_bf16_f32 v219, v118, v119
	v_add_f32_e32 v194, v194, v118
	v_add_f32_e32 v226, v226, v119
	v_mfma_f32_32x32x16_bf16 v[16:31], v[208:211], v[242:245], v[16:31]
	ds_read_b128 v[208:211], v173 offset:9248
	v_exp_f32_e32 v122, v122
	v_exp_f32_e32 v123, v123
	v_cvt_pk_bf16_f32 v234, v120, v121
	v_add_f32_e32 v194, v194, v120
	v_add_f32_e32 v226, v226, v121
	v_mfma_f32_32x32x16_bf16 v[128:143], v[92:95], v[108:111], v[128:143]
	ds_read_b128 v[92:95], v173 offset:4704
	v_exp_f32_e32 v124, v124
	v_exp_f32_e32 v125, v125
	v_cvt_pk_bf16_f32 v235, v122, v123
	v_add_f32_e32 v194, v194, v122
	v_add_f32_e32 v226, v226, v123
	v_mfma_f32_32x32x16_bf16 v[32:47], v[212:215], v[242:245], v[32:47]
	ds_read_b128 v[212:215], v173 offset:13856
	v_exp_f32_e32 v126, v126
	v_exp_f32_e32 v127, v127
	v_cvt_pk_bf16_f32 v236, v124, v125
	v_add_f32_e32 v194, v194, v124
	v_add_f32_e32 v226, v226, v125
	v_cvt_pk_bf16_f32 v237, v126, v127
	v_add_f32_e32 v194, v194, v126
	v_add_f32_e32 v226, v226, v127
	s_waitcnt vmcnt(0)
	v_add_u32_e32 v189, s28, v145
	ds_write_b128 v189, v[162:165]
	ds_write_b128 v189, v[166:169] offset:9216
	global_load_dwordx4 v[162:165], v[198:199], off
	global_load_dwordx4 v[166:169], v[196:197], off
	v_lshl_add_u64 v[198:199], v[198:199], 0, s[80:81]
	v_lshl_add_u64 v[196:197], v[196:197], 0, s[44:45]
	s_waitcnt lgkmcnt(8)
	v_mfma_f32_32x32x16_bf16 v[112:127], v[80:83], v[146:149], v[0:15]
	v_exp_f32_e32 v128, v128
	v_exp_f32_e32 v129, v129
	v_mfma_f32_32x32x16_bf16 v[48:63], v[200:203], v[216:219], v[48:63]
	v_exp_f32_e32 v130, v130
	v_exp_f32_e32 v131, v131
	v_cvt_pk_bf16_f32 v238, v128, v129
	v_add_f32_e32 v195, v195, v128
	v_add_f32_e32 v227, v227, v129
	s_waitcnt lgkmcnt(6)
	v_mfma_f32_32x32x16_bf16 v[112:127], v[84:87], v[150:153], v[112:127]
	v_exp_f32_e32 v132, v132
	v_exp_f32_e32 v133, v133
	v_cvt_pk_bf16_f32 v239, v130, v131
	v_add_f32_e32 v195, v195, v130
	v_add_f32_e32 v227, v227, v131
	v_mfma_f32_32x32x16_bf16 v[64:79], v[204:207], v[216:219], v[64:79]
	v_exp_f32_e32 v134, v134
	v_exp_f32_e32 v135, v135
	v_cvt_pk_bf16_f32 v240, v132, v133
	v_add_f32_e32 v195, v195, v132
	v_add_f32_e32 v227, v227, v133
	s_waitcnt lgkmcnt(4)
	v_mfma_f32_32x32x16_bf16 v[112:127], v[88:91], v[154:157], v[112:127]
	v_exp_f32_e32 v136, v136
	v_exp_f32_e32 v137, v137
	v_cvt_pk_bf16_f32 v241, v134, v135
	v_add_f32_e32 v195, v195, v134
	v_add_f32_e32 v227, v227, v135
	v_mfma_f32_32x32x16_bf16 v[48:63], v[208:211], v[234:237], v[48:63]
	v_exp_f32_e32 v138, v138
	v_exp_f32_e32 v139, v139
	v_cvt_pk_bf16_f32 v242, v136, v137
	v_add_f32_e32 v195, v195, v136
	v_add_f32_e32 v227, v227, v137
	s_waitcnt lgkmcnt(2)
	v_mfma_f32_32x32x16_bf16 v[112:127], v[92:95], v[158:161], v[112:127]
	v_exp_f32_e32 v140, v140
	v_exp_f32_e32 v141, v141
	v_cvt_pk_bf16_f32 v243, v138, v139
	v_add_f32_e32 v195, v195, v138
	v_add_f32_e32 v227, v227, v139
	v_mfma_f32_32x32x16_bf16 v[64:79], v[212:215], v[234:237], v[64:79]
	v_exp_f32_e32 v142, v142
	v_exp_f32_e32 v143, v143
	v_cvt_pk_bf16_f32 v244, v140, v141
	v_add_f32_e32 v195, v195, v140
	v_add_f32_e32 v227, v227, v141
	v_cvt_pk_bf16_f32 v245, v142, v143
	v_add_f32_e32 v195, v195, v142
	v_add_f32_e32 v227, v227, v143
	s_waitcnt lgkmcnt(0)
	s_barrier
; #define LAS __attribute__((address_space(3)))
; __device__ __forceinline__ void attn_unit(const bf16_t* Q, const bf16_t* K, const bf16_t* Vt, int ntiles, int nrows, bf16_t* O, float negM, LAS unsigned char* lds, int tid) {
;     ...
;     for (int t = 0; t < ntiles; ++t) {
;         const int cur = t & 1;
;         const bool more = (t + 1 < ntiles);
;         if (more) { kr = *(const u32x4*)(kg + (size_t)(t + 1) * 4096); vr = *(const u32x4*)(vg + (size_t)(t + 1) * 64); }
;         const LAS unsigned char* kb = lds + cur * 18432 + foff;
;         const LAS unsigned char* vb = kb + 9216;
;         bf16x8 kf0[4], kf1[4];
; #pragma unroll
;         for (int s = 0; s < 4; ++s) { kf0[s] = *(const LAS bf16x8*)(kb + s * 32); kf1[s] = *(const LAS bf16x8*)(kb + 32 * 144 + s * 32); }
;         bf16x8 pa[4], pb[4];
;         ATT_SCORES(qa, pa, lsa);
;         bf16x8 qc[4];
; #pragma unroll
;         for (int s = 0; s < 4; ++s) qc[s] = *(const LAS bf16x8*)(qlds + s * 1024);
;         ATT_SCORES(qc, pb, lsb);
; #pragma unroll
;         for (int s = 0; s < 4; ++s) {
;             const bf16x8 v0 = *(const LAS bf16x8*)(vb + s * 32), v1 = *(const LAS bf16x8*)(vb + 32 * 144 + s * 32);
;             oa0 = __builtin_amdgcn_mfma_f32_32x32x16_bf16(v0, pa[s], oa0, 0, 0, 0);
;             oa1 = __builtin_amdgcn_mfma_f32_32x32x16_bf16(v1, pa[s], oa1, 0, 0, 0);
;             ob0 = __builtin_amdgcn_mfma_f32_32x32x16_bf16(v0, pb[s], ob0, 0, 0, 0);
;             ob1 = __builtin_amdgcn_mfma_f32_32x32x16_bf16(v1, pb[s], ob1, 0, 0, 0);
;         }
;         if (more) { *(LAS u32x4*)(lds + (cur ^ 1) * 18432 + soff) = kr; *(LAS u32x4*)(lds + (cur ^ 1) * 18432 + 9216 + soff) = vr; }
;         __syncthreads();
;     }
	v_mfma_f32_32x32x16_bf16 v[128:143], v[80:83], v[96:99], v[0:15]
	ds_read_b128 v[80:83], v188
	v_exp_f32_e32 v112, v112
	v_exp_f32_e32 v113, v113
	v_mfma_f32_32x32x16_bf16 v[16:31], v[200:203], v[238:241], v[16:31]
	ds_read_b128 v[200:203], v173 offset:9280
	v_exp_f32_e32 v114, v114
	v_exp_f32_e32 v115, v115
	v_cvt_pk_bf16_f32 v216, v112, v113
	v_add_f32_e32 v194, v194, v112
	v_add_f32_e32 v226, v226, v113
	v_mfma_f32_32x32x16_bf16 v[128:143], v[84:87], v[100:103], v[128:143]
	ds_read_b128 v[84:87], v188 offset:32
	v_exp_f32_e32 v116, v116
	v_exp_f32_e32 v117, v117
	v_cvt_pk_bf16_f32 v217, v114, v115
	v_add_f32_e32 v194, v194, v114
	v_add_f32_e32 v226, v226, v115
	v_mfma_f32_32x32x16_bf16 v[32:47], v[204:207], v[238:241], v[32:47]
	ds_read_b128 v[204:207], v173 offset:13888
	v_exp_f32_e32 v118, v118
	v_exp_f32_e32 v119, v119
	v_cvt_pk_bf16_f32 v218, v116, v117
	v_add_f32_e32 v194, v194, v116
	v_add_f32_e32 v226, v226, v117
	v_mfma_f32_32x32x16_bf16 v[128:143], v[88:91], v[104:107], v[128:143]
	ds_read_b128 v[88:91], v188 offset:64
	v_exp_f32_e32 v120, v120
	v_exp_f32_e32 v121, v121
	v_cvt_pk_bf16_f32 v219, v118, v119
	v_add_f32_e32 v194, v194, v118
	v_add_f32_e32 v226, v226, v119
	v_mfma_f32_32x32x16_bf16 v[16:31], v[208:211], v[242:245], v[16:31]
	ds_read_b128 v[208:211], v173 offset:9312
	v_exp_f32_e32 v122, v122
	v_exp_f32_e32 v123, v123
	v_cvt_pk_bf16_f32 v234, v120, v121
	v_add_f32_e32 v194, v194, v120
	v_add_f32_e32 v226, v226, v121
	v_mfma_f32_32x32x16_bf16 v[128:143], v[92:95], v[108:111], v[128:143]
	ds_read_b128 v[92:95], v188 offset:96
	v_exp_f32_e32 v124, v124
	v_exp_f32_e32 v125, v125
	v_cvt_pk_bf16_f32 v235, v122, v123
	v_add_f32_e32 v194, v194, v122
	v_add_f32_e32 v226, v226, v123
	v_mfma_f32_32x32x16_bf16 v[32:47], v[212:215], v[242:245], v[32:47]
	ds_read_b128 v[212:215], v173 offset:13920
	v_exp_f32_e32 v126, v126
	v_exp_f32_e32 v127, v127
	v_cvt_pk_bf16_f32 v236, v124, v125
	v_add_f32_e32 v194, v194, v124
	v_add_f32_e32 v226, v226, v125
	v_cvt_pk_bf16_f32 v237, v126, v127
	v_add_f32_e32 v194, v194, v126
	v_add_f32_e32 v226, v226, v127
	s_waitcnt lgkmcnt(6)
	v_mfma_f32_32x32x16_bf16 v[112:127], v[80:83], v[146:149], v[0:15]
	v_exp_f32_e32 v128, v128
	v_exp_f32_e32 v129, v129
	v_mfma_f32_32x32x16_bf16 v[48:63], v[200:203], v[216:219], v[48:63]
	v_exp_f32_e32 v130, v130
	v_exp_f32_e32 v131, v131
	v_cvt_pk_bf16_f32 v238, v128, v129
	v_add_f32_e32 v195, v195, v128
	v_add_f32_e32 v227, v227, v129
	s_waitcnt lgkmcnt(4)
	v_mfma_f32_32x32x16_bf16 v[112:127], v[84:87], v[150:153], v[112:127]
	v_exp_f32_e32 v132, v132
	v_exp_f32_e32 v133, v133
	v_cvt_pk_bf16_f32 v239, v130, v131
	v_add_f32_e32 v195, v195, v130
	v_add_f32_e32 v227, v227, v131
	v_mfma_f32_32x32x16_bf16 v[64:79], v[204:207], v[216:219], v[64:79]
	v_exp_f32_e32 v134, v134
	v_exp_f32_e32 v135, v135
	v_cvt_pk_bf16_f32 v240, v132, v133
	v_add_f32_e32 v195, v195, v132
	v_add_f32_e32 v227, v227, v133
	s_waitcnt lgkmcnt(2)
	v_mfma_f32_32x32x16_bf16 v[112:127], v[88:91], v[154:157], v[112:127]
	v_exp_f32_e32 v136, v136
	v_exp_f32_e32 v137, v137
	v_cvt_pk_bf16_f32 v241, v134, v135
	v_add_f32_e32 v195, v195, v134
	v_add_f32_e32 v227, v227, v135
	v_mfma_f32_32x32x16_bf16 v[48:63], v[208:211], v[234:237], v[48:63]
	v_exp_f32_e32 v138, v138
	v_exp_f32_e32 v139, v139
	v_cvt_pk_bf16_f32 v242, v136, v137
	v_add_f32_e32 v195, v195, v136
	v_add_f32_e32 v227, v227, v137
	s_waitcnt lgkmcnt(0)
	v_mfma_f32_32x32x16_bf16 v[112:127], v[92:95], v[158:161], v[112:127]
	v_exp_f32_e32 v140, v140
	v_exp_f32_e32 v141, v141
	v_cvt_pk_bf16_f32 v243, v138, v139
	v_add_f32_e32 v195, v195, v138
	v_add_f32_e32 v227, v227, v139
	v_mfma_f32_32x32x16_bf16 v[64:79], v[212:215], v[234:237], v[64:79]
	v_exp_f32_e32 v142, v142
	v_exp_f32_e32 v143, v143
	v_cvt_pk_bf16_f32 v244, v140, v141
	v_add_f32_e32 v195, v195, v140
	v_add_f32_e32 v227, v227, v141
	v_cvt_pk_bf16_f32 v245, v142, v143
	v_add_f32_e32 v195, v195, v142
	v_add_f32_e32 v227, v227, v143
	v_mov_b32_e32 v173, v188
	s_add_i32 s28, s28, 0x4800
	s_cmp_eq_u32 s28, 0xd800
	s_cselect_b32 s28, 0, s28
	v_add_u32_e32 v188, s28, v181
	s_add_i32 s29, s29, 1
	s_cmp_lt_i32 s29, s13
	s_cbranch_scc1 .Lattn_tile
	s_waitcnt lgkmcnt(0)
	s_barrier
	v_mfma_f32_32x32x16_bf16 v[16:31], v[200:203], v[238:241], v[16:31]
	v_mfma_f32_32x32x16_bf16 v[32:47], v[204:207], v[238:241], v[32:47]
	v_mfma_f32_32x32x16_bf16 v[16:31], v[208:211], v[242:245], v[16:31]
	v_mfma_f32_32x32x16_bf16 v[32:47], v[212:215], v[242:245], v[32:47]
	v_add_f32_e32 v194, v194, v226
	v_add_f32_e32 v195, v195, v227
	s_nop 7
	s_nop 3

; __global__ void __launch_bounds__(NTHREADS, 2) mega(Params p) {
	.amdhsa_kernel _Z4mega6Params
		.amdhsa_group_segment_fixed_size 0
		.amdhsa_private_segment_fixed_size 0
		.amdhsa_kernarg_size 408
		.amdhsa_user_sgpr_count 2
		.amdhsa_user_sgpr_dispatch_ptr 0
		.amdhsa_user_sgpr_queue_ptr 0
		.amdhsa_user_sgpr_kernarg_segment_ptr 1
		.amdhsa_user_sgpr_dispatch_id 0
		.amdhsa_user_sgpr_kernarg_preload_length 0
		.amdhsa_user_sgpr_kernarg_preload_offset 0
		.amdhsa_user_sgpr_private_segment_size 0
		.amdhsa_uses_dynamic_stack 0
		.amdhsa_enable_private_segment 0
		.amdhsa_system_sgpr_workgroup_id_x 1
		.amdhsa_system_sgpr_workgroup_id_y 0
		.amdhsa_system_sgpr_workgroup_id_z 0
		.amdhsa_system_sgpr_workgroup_info 0
		.amdhsa_system_vgpr_workitem_id 2
		.amdhsa_next_free_vgpr 256
		.amdhsa_next_free_sgpr 102
		.amdhsa_accum_offset 256
		.amdhsa_reserve_vcc 1
		.amdhsa_float_round_mode_32 0
		.amdhsa_float_round_mode_16_64 0
		.amdhsa_float_denorm_mode_32 3
		.amdhsa_float_denorm_mode_16_64 3
		.amdhsa_dx10_clamp 1
		.amdhsa_ieee_mode 1
		.amdhsa_fp16_overflow 0
		.amdhsa_tg_split 0
		.amdhsa_exception_fp_ieee_invalid_op 0
		.amdhsa_exception_fp_denorm_src 0
		.amdhsa_exception_fp_ieee_div_zero 0
		.amdhsa_exception_fp_ieee_overflow 0
		.amdhsa_exception_fp_ieee_underflow 0
		.amdhsa_exception_fp_ieee_inexact 0
		.amdhsa_exception_int_div_zero 0
	.end_amdhsa_kernel

; __global__ void __launch_bounds__(NTHREADS, 2) mega(Params p) {
amdhsa.kernels:
  - .agpr_count:     0
    .args:
      - .offset:         0
        .size:           152
        .value_kind:     by_value
      - .offset:         152
        .size:           4
        .value_kind:     hidden_block_count_x
      - .offset:         156
        .size:           4
        .value_kind:     hidden_block_count_y
      - .offset:         160
        .size:           4
        .value_kind:     hidden_block_count_z
      - .offset:         164
        .size:           2
        .value_kind:     hidden_group_size_x
      - .offset:         166
        .size:           2
        .value_kind:     hidden_group_size_y
      - .offset:         168
        .size:           2
        .value_kind:     hidden_group_size_z
      - .offset:         170
        .size:           2
        .value_kind:     hidden_remainder_x
      - .offset:         172
        .size:           2
        .value_kind:     hidden_remainder_y
      - .offset:         174
        .size:           2
        .value_kind:     hidden_remainder_z
      - .offset:         192
        .size:           8
        .value_kind:     hidden_global_offset_x
      - .offset:         200
        .size:           8
        .value_kind:     hidden_global_offset_y
      - .offset:         208
        .size:           8
        .value_kind:     hidden_global_offset_z
      - .offset:         216
        .size:           2
        .value_kind:     hidden_grid_dims
      - .offset:         240
        .size:           8
        .value_kind:     hidden_multigrid_sync_arg
      - .offset:         272
        .size:           4
        .value_kind:     hidden_dynamic_lds_size
    .group_segment_fixed_size: 0
    .kernarg_segment_align: 8
    .kernarg_segment_size: 408
    .language:       OpenCL C
    .language_version:
      - 2
      - 0
    .max_flat_workgroup_size: 512
    .name:           _Z4mega6Params
    .private_segment_fixed_size: 0
    .sgpr_count:     108
    .sgpr_spill_count: 247
    .symbol:         _Z4mega6Params.kd
    .uniform_work_group_size: 1
    .uses_dynamic_stack: false
    .vgpr_count:     256
    .vgpr_spill_count: 0
    .wavefront_size: 64
